# cvt loop L2 prefetch 2 items ahead (one lane per row line) in phase-1 weight conversion, on top of v40
# speedup vs baseline: 1.0037x; 1.0037x over previous
.Lpf_up_nok:
	s_lshl_b32 s38, s0, 1
	s_add_i32 s38, s38, s1
	s_min_i32 s38, s38, 0x62ff
	v_mov_b32_e32 v247, 0
	s_cmpk_lt_i32 s38, 0x2300
	s_cbranch_scc1 .Lpfo_wn
	s_cmpk_lt_i32 s38, 0x4300
	s_cbranch_scc1 .Lpfu_wn
	s_add_i32 s38, s38, 0xffffbd00
	s_and_b32 s39, s38, 0x7fffffc0
	s_and_b32 s38, s38, 63
	s_lshl_b32 s38, s38, 7
	v_add_u32_e32 v246, s39, v249
	v_lshlrev_b32_e32 v246, 13, v246
	v_add_u32_e32 v246, s38, v246
	v_lshl_add_u64 v[246:247], s[2:3], 0, v[246:247]
	s_branch .Lpfj_wn
.Lpfu_wn:
	s_add_i32 s38, s38, 0xffffdd00
	s_lshr_b32 s39, s38, 8
	s_lshl_b32 s39, s39, 6
	s_and_b32 s38, s38, 0xff
	s_lshl_b32 s38, s38, 7
	v_add_u32_e32 v246, s39, v249
	v_lshlrev_b32_e32 v246, 15, v246
	v_add_u32_e32 v246, s38, v246
	v_lshl_add_u64 v[246:247], s[14:15], 0, v[246:247]
	s_branch .Lpfj_wn
.Lpfo_wn:
	s_add_i32 s38, s38, 0xffffe500
	s_and_b32 s39, s38, 0x7fffffc0
	s_and_b32 s38, s38, 63
	s_lshl_b32 s38, s38, 7
	v_add_u32_e32 v246, s39, v249
	v_lshlrev_b32_e32 v246, 13, v246
	v_add_u32_e32 v246, s38, v246
	v_lshl_add_u64 v[246:247], s[40:41], 0, v[246:247]
.Lpfj_wn:
	global_load_dword v248, v[246:247], off
	s_branch .LBB0_1073
.Lp1_cvt:
	s_add_i32 s0, s20, 0xfffffd00
	s_cmpk_gt_i32 s0, 0x47ff
	s_cbranch_scc1 .LBB0_1145
	v_mbcnt_lo_u32_b32 v249, -1, 0
	v_mbcnt_hi_u32_b32 v249, -1, v249
	s_load_dwordx8 s[40:47], s[70:71], 0xc8
	s_lshl_b32 s2, s75, 14
	v_and_b32_e32 v50, 31, v235
	v_lshrrev_b32_e32 v51, 5, v234
	v_readlane_b32 s0, v255, 17
	s_add_i32 s18, s2, 0
	v_lshlrev_b32_e32 v6, 2, v50
	s_waitcnt lgkmcnt(0)
	v_mul_u32_u24_e32 v7, 0x84, v51
	v_readlane_b32 s1, v255, 18
	s_mov_b32 s21, s75
	s_ashr_i32 s75, s74, 31
	v_add3_u32 v52, s18, v6, v7
	v_lshlrev_b32_e32 v6, 3, v234
	s_addk_i32 s0, 0xfd00
	s_add_i32 s1, s20, 0x1800
	s_lshl_b64 s[4:5], s[74:75], 26
	v_and_b32_e32 v6, 56, v6
	s_add_u32 s2, s46, s4
	v_lshlrev_b32_e32 v190, 1, v6
	s_addc_u32 s3, s47, s5
	v_lshl_add_u64 v[10:11], s[12:13], 0, v[190:191]
	s_mov_b64 s[14:15], 0x4400000
	v_mul_u32_u24_e32 v8, 0x84, v6
	v_lshl_add_u64 v[6:7], v[10:11], 0, s[14:15]
	s_add_u32 s14, s44, s4
	v_lshrrev_b32_e32 v53, 3, v234
	s_addc_u32 s15, s45, s5
	v_lshlrev_b32_e32 v9, 2, v53
	s_cmp_lg_u64 s[42:43], 0
	v_add3_u32 v54, s18, v8, v9
	s_cselect_b64 s[18:19], -1, 0
	s_lshl_b64 s[4:5], s[74:75], 13
	s_load_dwordx4 s[52:55], s[70:71], 0x8
	s_add_u32 s36, s42, s4
	s_mov_b64 s[38:39], 0x2400000
	s_addc_u32 s37, s43, s5
	v_lshl_add_u64 v[8:9], v[10:11], 0, s[38:39]
	s_lshl_b64 s[38:39], s[74:75], 24
	s_add_u32 s40, s40, s38
	s_addc_u32 s41, s41, s39
	s_mul_i32 s23, s74, 0x3560000
	s_mov_b32 s75, s21
	s_mul_hi_i32 s21, s74, 0x3560000
	s_waitcnt lgkmcnt(0)
	s_add_u32 s42, s54, s23
	s_addc_u32 s43, s55, s21
	s_add_u32 s44, s52, s4
	s_addc_u32 s45, s53, s5
	s_mov_b64 s[38:39], 0x1c00000
	s_cmp_lg_u64 s[52:53], 0
	v_or_b32_e32 v55, 8, v53
	v_or_b32_e32 v56, 16, v53
	v_or_b32_e32 v57, 24, v53
	v_lshl_add_u64 v[10:11], v[10:11], 0, s[38:39]
	s_cselect_b64 s[46:47], -1, 0
	v_lshl_add_u64 v[12:13], s[48:49], 0, v[190:191]
	s_lshl_b32 s21, s1, 5
	s_lshl_b32 s23, s0, 5
	s_branch .LBB0_1066

.LBB0_1066:
	s_cmpk_gt_i32 s1, 0x1aff
	s_mov_b64 s[4:5], -1
	s_cbranch_scc0 .LBB0_1078
	s_cmpk_gt_u32 s1, 0x22ff
	s_cbranch_scc0 .LBB0_1075
	s_cmpk_gt_u32 s1, 0x42ff
	s_cbranch_scc0 .LBB0_1070
	s_and_b32 s4, s1, 0x7fffffc0
	s_add_i32 s26, s4, 0xffffbd00
	s_and_b32 s4, s21, 0x7e0
	v_or_b32_e32 v190, s26, v51
	v_or_b32_e32 v16, s4, v50
	v_lshlrev_b64 v[14:15], 13, v[190:191]
	v_lshl_add_u64 v[14:15], s[2:3], 0, v[14:15]
	v_lshlrev_b32_e32 v190, 2, v16
	v_lshl_add_u64 v[14:15], v[14:15], 0, v[190:191]
	v_add_co_u32_e32 v16, vcc, 0x4000, v14
	global_load_dword v18, v[14:15], off nt
	s_nop 0
	v_addc_co_u32_e32 v17, vcc, 0, v15, vcc
	global_load_dword v19, v[16:17], off nt
	v_add_co_u32_e32 v16, vcc, 0x8000, v14
	s_mov_b32 s5, 0x10000
	s_nop 0
	v_addc_co_u32_e32 v17, vcc, 0, v15, vcc
	global_load_dword v20, v[16:17], off nt
	v_add_co_u32_e32 v16, vcc, 0xc000, v14
	s_nop 1
	v_addc_co_u32_e32 v17, vcc, 0, v15, vcc
	global_load_dword v21, v[16:17], off nt
	v_add_co_u32_e32 v16, vcc, s5, v14
	s_mov_b32 s5, 0x14000
	s_nop 0
	v_addc_co_u32_e32 v17, vcc, 0, v15, vcc
	global_load_dword v22, v[16:17], off nt
	v_add_co_u32_e32 v16, vcc, s5, v14
	s_mov_b32 s5, 0x18000
	s_nop 0
	v_addc_co_u32_e32 v17, vcc, 0, v15, vcc
	global_load_dword v23, v[16:17], off nt
	v_add_co_u32_e32 v16, vcc, s5, v14
	s_mov_b32 s5, 0x1c000
	s_nop 0
	v_addc_co_u32_e32 v17, vcc, 0, v15, vcc
	global_load_dword v24, v[16:17], off nt
	v_add_co_u32_e32 v16, vcc, s5, v14
	s_mov_b32 s5, 0x20000
	s_nop 0
	v_addc_co_u32_e32 v17, vcc, 0, v15, vcc
	global_load_dword v25, v[16:17], off nt
	v_add_co_u32_e32 v16, vcc, s5, v14
	s_mov_b32 s5, 0x24000
	s_nop 0
	v_addc_co_u32_e32 v17, vcc, 0, v15, vcc
	global_load_dword v26, v[16:17], off nt
	v_add_co_u32_e32 v16, vcc, s5, v14
	s_mov_b32 s5, 0x28000
	s_nop 0
	v_addc_co_u32_e32 v17, vcc, 0, v15, vcc
	global_load_dword v27, v[16:17], off nt
	v_add_co_u32_e32 v16, vcc, s5, v14
	s_mov_b32 s5, 0x2c000
	s_nop 0
	v_addc_co_u32_e32 v17, vcc, 0, v15, vcc
	global_load_dword v28, v[16:17], off nt
	v_add_co_u32_e32 v16, vcc, s5, v14
	s_mov_b32 s5, 0x30000
	s_nop 0
	v_addc_co_u32_e32 v17, vcc, 0, v15, vcc
	global_load_dword v29, v[16:17], off nt
	v_add_co_u32_e32 v16, vcc, s5, v14
	s_mov_b32 s5, 0x34000
	s_nop 0
	v_addc_co_u32_e32 v17, vcc, 0, v15, vcc
	global_load_dword v30, v[16:17], off nt
	v_add_co_u32_e32 v16, vcc, s5, v14
	s_mov_b32 s5, 0x38000
	s_nop 0
	v_addc_co_u32_e32 v17, vcc, 0, v15, vcc
	global_load_dword v31, v[16:17], off nt
	v_add_co_u32_e32 v16, vcc, s5, v14
	s_mov_b32 s5, 0x3c000
	s_nop 0
	v_addc_co_u32_e32 v17, vcc, 0, v15, vcc
	global_load_dword v32, v[16:17], off nt
	v_add_co_u32_e32 v16, vcc, s5, v14
	s_mov_b32 s5, 0x40000
	s_nop 0
	v_addc_co_u32_e32 v17, vcc, 0, v15, vcc
	global_load_dword v33, v[16:17], off nt
	v_add_co_u32_e32 v16, vcc, s5, v14
	s_mov_b32 s5, 0x44000
	s_nop 0
	v_addc_co_u32_e32 v17, vcc, 0, v15, vcc
	global_load_dword v34, v[16:17], off nt
	v_add_co_u32_e32 v16, vcc, s5, v14
	s_mov_b32 s5, 0x48000
	s_nop 0
	v_addc_co_u32_e32 v17, vcc, 0, v15, vcc
	global_load_dword v35, v[16:17], off nt
	v_add_co_u32_e32 v16, vcc, s5, v14
	s_mov_b32 s5, 0x4c000
	s_nop 0
	v_addc_co_u32_e32 v17, vcc, 0, v15, vcc
	global_load_dword v36, v[16:17], off nt
	v_add_co_u32_e32 v16, vcc, s5, v14
	s_mov_b32 s5, 0x50000
	s_nop 0
	v_addc_co_u32_e32 v17, vcc, 0, v15, vcc
	global_load_dword v37, v[16:17], off nt
	v_add_co_u32_e32 v16, vcc, s5, v14
	s_mov_b32 s5, 0x54000
	s_nop 0
	v_addc_co_u32_e32 v17, vcc, 0, v15, vcc
	global_load_dword v38, v[16:17], off nt
	v_add_co_u32_e32 v16, vcc, s5, v14
	s_mov_b32 s5, 0x58000
	s_nop 0
	v_addc_co_u32_e32 v17, vcc, 0, v15, vcc
	global_load_dword v39, v[16:17], off nt
	v_add_co_u32_e32 v16, vcc, s5, v14
	s_mov_b32 s5, 0x5c000
	s_nop 0
	v_addc_co_u32_e32 v17, vcc, 0, v15, vcc
	global_load_dword v40, v[16:17], off nt
	v_add_co_u32_e32 v16, vcc, s5, v14
	s_mov_b32 s5, 0x60000
	s_nop 0
	v_addc_co_u32_e32 v17, vcc, 0, v15, vcc
	global_load_dword v41, v[16:17], off nt
	v_add_co_u32_e32 v16, vcc, s5, v14
	s_mov_b32 s5, 0x64000
	s_nop 0
	v_addc_co_u32_e32 v17, vcc, 0, v15, vcc
	global_load_dword v42, v[16:17], off nt
	v_add_co_u32_e32 v16, vcc, s5, v14
	s_mov_b32 s5, 0x68000
	s_nop 0
	v_addc_co_u32_e32 v17, vcc, 0, v15, vcc
	global_load_dword v43, v[16:17], off nt
	v_add_co_u32_e32 v16, vcc, s5, v14
	s_mov_b32 s5, 0x6c000
	s_nop 0
	v_addc_co_u32_e32 v17, vcc, 0, v15, vcc
	global_load_dword v44, v[16:17], off nt
	v_add_co_u32_e32 v16, vcc, s5, v14
	s_mov_b32 s5, 0x70000
	s_nop 0
	v_addc_co_u32_e32 v17, vcc, 0, v15, vcc
	global_load_dword v45, v[16:17], off nt
	v_add_co_u32_e32 v16, vcc, s5, v14
	s_mov_b32 s5, 0x74000
	s_nop 0
	v_addc_co_u32_e32 v17, vcc, 0, v15, vcc
	global_load_dword v46, v[16:17], off nt
	v_add_co_u32_e32 v16, vcc, s5, v14
	s_mov_b32 s5, 0x78000
	s_nop 0
	v_addc_co_u32_e32 v17, vcc, 0, v15, vcc
	global_load_dword v47, v[16:17], off nt
	v_add_co_u32_e32 v16, vcc, s5, v14
	s_mov_b32 s5, 0x7c000
	s_nop 0
	v_addc_co_u32_e32 v17, vcc, 0, v15, vcc
	v_add_co_u32_e32 v14, vcc, s5, v14
	global_load_dword v16, v[16:17], off nt
	s_nop 0
	v_addc_co_u32_e32 v15, vcc, 0, v15, vcc
	global_load_dword v14, v[14:15], off nt
	v_add_u32_e32 v15, 0x400, v52
	s_lshl_b32 s38, s0, 1
	s_add_i32 s38, s38, s1
	s_min_i32 s38, s38, 0x62ff
	v_mov_b32_e32 v247, 0
	s_cmpk_lt_i32 s38, 0x2300
	s_cbranch_scc1 .Lpfo_wd
	s_cmpk_lt_i32 s38, 0x4300
	s_cbranch_scc1 .Lpfu_wd
	s_add_i32 s38, s38, 0xffffbd00
	s_and_b32 s39, s38, 0x7fffffc0
	s_and_b32 s38, s38, 63
	s_lshl_b32 s38, s38, 7
	v_add_u32_e32 v246, s39, v249
	v_lshlrev_b32_e32 v246, 13, v246
	v_add_u32_e32 v246, s38, v246
	v_lshl_add_u64 v[246:247], s[2:3], 0, v[246:247]
	s_branch .Lpfj_wd

.Lpfj_wd:
	global_load_dword v248, v[246:247], off
	s_waitcnt vmcnt(31)
	ds_write2_b32 v52, v18, v19 offset1:66
	s_waitcnt vmcnt(29)
	ds_write2_b32 v52, v20, v21 offset0:132 offset1:198
	s_waitcnt vmcnt(27)
	ds_write2_b32 v15, v22, v23 offset0:8 offset1:74
	s_waitcnt vmcnt(25)
	ds_write2_b32 v15, v24, v25 offset0:140 offset1:206
	v_add_u32_e32 v15, 0x800, v52
	s_waitcnt vmcnt(23)
	ds_write2_b32 v15, v26, v27 offset0:16 offset1:82
	s_waitcnt vmcnt(21)
	ds_write2_b32 v15, v28, v29 offset0:148 offset1:214
	v_add_u32_e32 v15, 0xc00, v52
	s_waitcnt vmcnt(19)
	ds_write2_b32 v15, v30, v31 offset0:24 offset1:90
	s_waitcnt vmcnt(17)
	ds_write2_b32 v15, v32, v33 offset0:156 offset1:222
	v_add_u32_e32 v15, 0x1000, v52
	s_waitcnt vmcnt(15)
	ds_write2_b32 v15, v34, v35 offset0:32 offset1:98
	s_waitcnt vmcnt(13)
	ds_write2_b32 v15, v36, v37 offset0:164 offset1:230
	v_add_u32_e32 v15, 0x1400, v52
	s_waitcnt vmcnt(11)
	ds_write2_b32 v15, v38, v39 offset0:40 offset1:106
	s_waitcnt vmcnt(9)
	ds_write2_b32 v15, v40, v41 offset0:172 offset1:238
	v_add_u32_e32 v15, 0x1800, v52
	s_waitcnt vmcnt(7)
	ds_write2_b32 v15, v42, v43 offset0:48 offset1:114
	s_waitcnt vmcnt(5)
	ds_write2_b32 v15, v44, v45 offset0:180 offset1:246
	v_add_u32_e32 v15, 0x1c00, v52
	s_waitcnt vmcnt(3)
	ds_write2_b32 v15, v46, v47 offset0:56 offset1:122
	s_waitcnt vmcnt(1)
	ds_write2_b32 v15, v16, v14 offset0:188 offset1:254
	s_waitcnt lgkmcnt(0)
	ds_read2_b32 v[20:21], v54 offset0:33 offset1:41
	ds_read2_b32 v[22:23], v54 offset1:8
	ds_read2_b32 v[24:25], v54 offset0:66 offset1:74
	ds_read2_b32 v[26:27], v54 offset0:99 offset1:107
	ds_read2_b32 v[28:29], v54 offset0:132 offset1:140
	ds_read2_b32 v[30:31], v54 offset0:165 offset1:173
	ds_read2_b32 v[32:33], v54 offset0:198 offset1:206
	ds_read2_b32 v[34:35], v54 offset0:231 offset1:239
	v_lshl_add_u64 v[18:19], s[26:27], 1, v[6:7]
	s_waitcnt lgkmcnt(6)
	v_cvt_pk_bf16_f32 v14, v22, v20
	v_or_b32_e32 v20, s4, v53
	v_lshlrev_b32_e32 v190, 14, v20
	v_or_b32_e32 v20, s4, v55
	s_waitcnt lgkmcnt(4)
	v_cvt_pk_bf16_f32 v15, v24, v26
	s_waitcnt lgkmcnt(2)
	v_cvt_pk_bf16_f32 v16, v28, v30
	s_waitcnt lgkmcnt(0)
	v_cvt_pk_bf16_f32 v17, v32, v34
	v_lshl_add_u64 v[36:37], v[18:19], 0, v[190:191]
	v_lshlrev_b32_e32 v190, 14, v20
	global_store_dwordx4 v[36:37], v[14:17], off nt
	s_nop 1
	v_cvt_pk_bf16_f32 v14, v23, v21
	v_cvt_pk_bf16_f32 v15, v25, v27
	v_cvt_pk_bf16_f32 v16, v29, v31
	v_cvt_pk_bf16_f32 v17, v33, v35
	v_lshl_add_u64 v[20:21], v[18:19], 0, v[190:191]
	global_store_dwordx4 v[20:21], v[14:17], off nt
	ds_read2_b32 v[20:21], v54 offset0:49 offset1:57
	ds_read2_b32 v[22:23], v54 offset0:16 offset1:24
	ds_read2_b32 v[24:25], v54 offset0:82 offset1:90
	ds_read2_b32 v[26:27], v54 offset0:115 offset1:123
	ds_read2_b32 v[28:29], v54 offset0:148 offset1:156
	ds_read2_b32 v[30:31], v54 offset0:181 offset1:189
	ds_read2_b32 v[32:33], v54 offset0:214 offset1:222
	ds_read2_b32 v[34:35], v54 offset0:247 offset1:255
	s_waitcnt lgkmcnt(6)
	v_cvt_pk_bf16_f32 v14, v22, v20
	v_or_b32_e32 v20, s4, v56
	v_lshlrev_b32_e32 v190, 14, v20
	v_or_b32_e32 v20, s4, v57
	s_waitcnt lgkmcnt(4)
	v_cvt_pk_bf16_f32 v15, v24, v26
	s_waitcnt lgkmcnt(2)
	v_cvt_pk_bf16_f32 v16, v28, v30
	s_waitcnt lgkmcnt(0)
	v_cvt_pk_bf16_f32 v17, v32, v34
	v_lshl_add_u64 v[36:37], v[18:19], 0, v[190:191]
	v_lshlrev_b32_e32 v190, 14, v20
	global_store_dwordx4 v[36:37], v[14:17], off nt
	v_lshl_add_u64 v[18:19], v[18:19], 0, v[190:191]
	s_mov_b64 s[4:5], 0
	v_cvt_pk_bf16_f32 v14, v23, v21
	v_cvt_pk_bf16_f32 v15, v25, v27
	v_cvt_pk_bf16_f32 v16, v29, v31
	v_cvt_pk_bf16_f32 v17, v33, v35
	global_store_dwordx4 v[18:19], v[14:17], off nt
	s_waitcnt lgkmcnt(0)
.LBB0_1070:
	s_andn2_b64 vcc, exec, s[4:5]
	s_cbranch_vccnz .LBB0_1074
	s_add_i32 s4, s1, 0xdd00
	s_bfe_u32 s4, s4, 0x80008
	s_lshl_b32 s5, s4, 6
	s_and_b32 s4, s21, 0x1fe0
	s_waitcnt vmcnt(12)
	v_or_b32_e32 v48, s5, v51
	v_or_b32_e32 v16, s4, v50
	v_lshlrev_b32_e32 v190, 15, v48
	v_lshl_add_u64 v[14:15], s[14:15], 0, v[190:191]
	v_lshlrev_b32_e32 v190, 2, v16
	v_lshl_add_u64 v[38:39], v[14:15], 0, v[190:191]
	v_add_co_u32_e32 v16, vcc, 0x10000, v38
	global_load_dword v14, v[38:39], off nt
	s_nop 0
	v_addc_co_u32_e32 v17, vcc, 0, v39, vcc
	global_load_dword v15, v[16:17], off nt
	v_add_co_u32_e32 v16, vcc, 0x20000, v38
	s_nop 1
	v_addc_co_u32_e32 v17, vcc, 0, v39, vcc
	v_add_co_u32_e32 v18, vcc, 0x30000, v38
	global_load_dword v16, v[16:17], off nt
	s_nop 0
	v_addc_co_u32_e32 v19, vcc, 0, v39, vcc
	global_load_dword v17, v[18:19], off nt
	v_add_co_u32_e32 v18, vcc, 0x40000, v38
	s_nop 1
	v_addc_co_u32_e32 v19, vcc, 0, v39, vcc
	v_add_co_u32_e32 v20, vcc, 0x50000, v38
	global_load_dword v18, v[18:19], off nt
	s_nop 0
	v_addc_co_u32_e32 v21, vcc, 0, v39, vcc
	global_load_dword v19, v[20:21], off nt
	v_add_co_u32_e32 v20, vcc, 0x60000, v38
	s_nop 1
	v_addc_co_u32_e32 v21, vcc, 0, v39, vcc
	v_add_co_u32_e32 v22, vcc, 0x70000, v38
	global_load_dword v20, v[20:21], off nt
	s_nop 0
	v_addc_co_u32_e32 v23, vcc, 0, v39, vcc
	global_load_dword v21, v[22:23], off nt
	v_add_co_u32_e32 v22, vcc, 0x80000, v38
	s_nop 1
	v_addc_co_u32_e32 v23, vcc, 0, v39, vcc
	v_add_co_u32_e32 v24, vcc, 0x90000, v38
	global_load_dword v22, v[22:23], off nt
	s_nop 0
	v_addc_co_u32_e32 v25, vcc, 0, v39, vcc
	global_load_dword v23, v[24:25], off nt
	v_add_co_u32_e32 v24, vcc, 0xa0000, v38
	s_nop 1
	v_addc_co_u32_e32 v25, vcc, 0, v39, vcc
	v_add_co_u32_e32 v26, vcc, 0xb0000, v38
	global_load_dword v24, v[24:25], off nt
	s_nop 0
	v_addc_co_u32_e32 v27, vcc, 0, v39, vcc
	global_load_dword v25, v[26:27], off nt
	v_add_co_u32_e32 v26, vcc, 0xc0000, v38
	s_nop 1
	v_addc_co_u32_e32 v27, vcc, 0, v39, vcc
	v_add_co_u32_e32 v28, vcc, 0xd0000, v38
	global_load_dword v26, v[26:27], off nt
	s_nop 0
	v_addc_co_u32_e32 v29, vcc, 0, v39, vcc
	global_load_dword v27, v[28:29], off nt
	v_add_co_u32_e32 v28, vcc, 0xe0000, v38
	s_nop 1
	v_addc_co_u32_e32 v29, vcc, 0, v39, vcc
	v_add_co_u32_e32 v30, vcc, 0xf0000, v38
	global_load_dword v28, v[28:29], off nt
	s_nop 0
	v_addc_co_u32_e32 v31, vcc, 0, v39, vcc
	global_load_dword v29, v[30:31], off nt
	v_add_co_u32_e32 v30, vcc, 0x100000, v38
	s_nop 1
	v_addc_co_u32_e32 v31, vcc, 0, v39, vcc
	v_add_co_u32_e32 v32, vcc, 0x110000, v38
	global_load_dword v30, v[30:31], off nt
	s_nop 0
	v_addc_co_u32_e32 v33, vcc, 0, v39, vcc
	global_load_dword v31, v[32:33], off nt
	v_add_co_u32_e32 v32, vcc, 0x120000, v38
	s_nop 1
	v_addc_co_u32_e32 v33, vcc, 0, v39, vcc
	v_add_co_u32_e32 v34, vcc, 0x130000, v38
	global_load_dword v32, v[32:33], off nt
	s_nop 0
	v_addc_co_u32_e32 v35, vcc, 0, v39, vcc
	global_load_dword v33, v[34:35], off nt
	v_add_co_u32_e32 v34, vcc, 0x140000, v38
	s_nop 1
	v_addc_co_u32_e32 v35, vcc, 0, v39, vcc
	v_add_co_u32_e32 v36, vcc, 0x150000, v38
	global_load_dword v34, v[34:35], off nt
	s_nop 0
	v_addc_co_u32_e32 v37, vcc, 0, v39, vcc
	global_load_dword v35, v[36:37], off nt
	v_add_co_u32_e32 v36, vcc, 0x160000, v38
	s_nop 1
	v_addc_co_u32_e32 v37, vcc, 0, v39, vcc
	v_add_co_u32_e32 v40, vcc, 0x170000, v38
	global_load_dword v36, v[36:37], off nt
	s_nop 0
	v_addc_co_u32_e32 v41, vcc, 0, v39, vcc
	global_load_dword v37, v[40:41], off nt
	v_add_co_u32_e32 v40, vcc, 0x180000, v38
	s_nop 1
	v_addc_co_u32_e32 v41, vcc, 0, v39, vcc
	s_waitcnt vmcnt(35)
	v_add_co_u32_e32 v42, vcc, 0x190000, v38
	global_load_dword v40, v[40:41], off nt
	s_nop 0
	v_addc_co_u32_e32 v43, vcc, 0, v39, vcc
	global_load_dword v41, v[42:43], off nt
	v_add_co_u32_e32 v42, vcc, 0x1a0000, v38
	s_nop 1
	v_addc_co_u32_e32 v43, vcc, 0, v39, vcc
	v_add_co_u32_e32 v44, vcc, 0x1b0000, v38
	global_load_dword v42, v[42:43], off nt
	s_nop 0
	v_addc_co_u32_e32 v45, vcc, 0, v39, vcc
	global_load_dword v43, v[44:45], off nt
	v_add_co_u32_e32 v44, vcc, 0x1c0000, v38
	s_nop 1
	v_addc_co_u32_e32 v45, vcc, 0, v39, vcc
	v_add_co_u32_e32 v46, vcc, 0x1d0000, v38
	global_load_dword v44, v[44:45], off nt
	s_nop 0
	v_addc_co_u32_e32 v47, vcc, 0, v39, vcc
	global_load_dword v45, v[46:47], off nt
	v_add_co_u32_e32 v46, vcc, 0x1e0000, v38
	s_nop 1
	v_addc_co_u32_e32 v47, vcc, 0, v39, vcc
	v_add_co_u32_e32 v38, vcc, 0x1f0000, v38
	global_load_dword v46, v[46:47], off nt
	s_nop 0
	v_addc_co_u32_e32 v39, vcc, 0, v39, vcc
	global_load_dword v47, v[38:39], off nt
	s_andn2_b64 vcc, exec, s[18:19]
	s_cbranch_vccnz .Lpf_up_nok
	s_waitcnt vmcnt(36)
	v_lshlrev_b32_e32 v85, 2, v48
	global_load_dword v38, v85, s[36:37]
	global_load_dword v39, v85, s[36:37] offset:8
	global_load_dword v48, v85, s[36:37] offset:16
	global_load_dword v49, v85, s[36:37] offset:24
	global_load_dword v58, v85, s[36:37] offset:32
	global_load_dword v59, v85, s[36:37] offset:40
	global_load_dword v60, v85, s[36:37] offset:48
	global_load_dword v61, v85, s[36:37] offset:56
	global_load_dword v62, v85, s[36:37] offset:64
	global_load_dword v63, v85, s[36:37] offset:72
	global_load_dword v64, v85, s[36:37] offset:80
	global_load_dword v65, v85, s[36:37] offset:88
	global_load_dword v66, v85, s[36:37] offset:96
	global_load_dword v67, v85, s[36:37] offset:104
	global_load_dword v68, v85, s[36:37] offset:112
	global_load_dword v69, v85, s[36:37] offset:120
	global_load_dword v70, v85, s[36:37] offset:128
	global_load_dword v71, v85, s[36:37] offset:136
	global_load_dword v72, v85, s[36:37] offset:144
	global_load_dword v73, v85, s[36:37] offset:152
	global_load_dword v74, v85, s[36:37] offset:160
	global_load_dword v75, v85, s[36:37] offset:168
	global_load_dword v76, v85, s[36:37] offset:176
	global_load_dword v77, v85, s[36:37] offset:184
	global_load_dword v78, v85, s[36:37] offset:192
	global_load_dword v79, v85, s[36:37] offset:200
	global_load_dword v80, v85, s[36:37] offset:208
	global_load_dword v81, v85, s[36:37] offset:216
	global_load_dword v82, v85, s[36:37] offset:224
	global_load_dword v83, v85, s[36:37] offset:232
	global_load_dword v84, v85, s[36:37] offset:240
	s_nop 0
	global_load_dword v85, v85, s[36:37] offset:248
	s_lshl_b32 s38, s0, 1
	s_add_i32 s38, s38, s1
	s_min_i32 s38, s38, 0x62ff
	v_mov_b32_e32 v247, 0
	s_cmpk_lt_i32 s38, 0x2300
	s_cbranch_scc1 .Lpfo_wu
	s_cmpk_lt_i32 s38, 0x4300
	s_cbranch_scc1 .Lpfu_wu
	s_add_i32 s38, s38, 0xffffbd00
	s_and_b32 s39, s38, 0x7fffffc0
	s_and_b32 s38, s38, 63
	s_lshl_b32 s38, s38, 7
	v_add_u32_e32 v246, s39, v249
	v_lshlrev_b32_e32 v246, 13, v246
	v_add_u32_e32 v246, s38, v246
	v_lshl_add_u64 v[246:247], s[2:3], 0, v[246:247]
	s_branch .Lpfj_wu

.Lpfj_wu:
	global_load_dword v248, v[246:247], off
	s_waitcnt vmcnt(31)
	v_pk_mul_f32 v[14:15], v[14:15], v[38:39]
	s_waitcnt vmcnt(29)
	v_pk_mul_f32 v[16:17], v[16:17], v[48:49]
	s_waitcnt vmcnt(27)
	v_pk_mul_f32 v[18:19], v[18:19], v[58:59]
	s_waitcnt vmcnt(25)
	v_pk_mul_f32 v[20:21], v[20:21], v[60:61]
	s_waitcnt vmcnt(23)
	v_pk_mul_f32 v[22:23], v[22:23], v[62:63]
	s_waitcnt vmcnt(21)
	v_pk_mul_f32 v[24:25], v[24:25], v[64:65]
	s_waitcnt vmcnt(19)
	v_pk_mul_f32 v[26:27], v[26:27], v[66:67]
	s_waitcnt vmcnt(17)
	v_pk_mul_f32 v[28:29], v[28:29], v[68:69]
	s_waitcnt vmcnt(15)
	v_pk_mul_f32 v[30:31], v[30:31], v[70:71]
	s_waitcnt vmcnt(13)
	v_pk_mul_f32 v[32:33], v[32:33], v[72:73]
	s_waitcnt vmcnt(11)
	v_pk_mul_f32 v[34:35], v[34:35], v[74:75]
	s_waitcnt vmcnt(9)
	v_pk_mul_f32 v[36:37], v[36:37], v[76:77]
	s_waitcnt vmcnt(7)
	v_pk_mul_f32 v[40:41], v[40:41], v[78:79]
	s_waitcnt vmcnt(5)
	v_pk_mul_f32 v[42:43], v[42:43], v[80:81]
	s_waitcnt vmcnt(3)
	v_pk_mul_f32 v[44:45], v[44:45], v[82:83]
	s_waitcnt vmcnt(1)
	v_pk_mul_f32 v[46:47], v[46:47], v[84:85]
.LBB0_1073:
	s_waitcnt vmcnt(31)
	ds_write2_b32 v52, v14, v15 offset1:66
	s_waitcnt vmcnt(29)
	ds_write2_b32 v52, v16, v17 offset0:132 offset1:198
	v_add_u32_e32 v14, 0x400, v52
	s_waitcnt vmcnt(27)
	ds_write2_b32 v14, v18, v19 offset0:8 offset1:74
	s_waitcnt vmcnt(25)
	ds_write2_b32 v14, v20, v21 offset0:140 offset1:206
	v_add_u32_e32 v14, 0x800, v52
	s_waitcnt vmcnt(23)
	ds_write2_b32 v14, v22, v23 offset0:16 offset1:82
	s_waitcnt vmcnt(21)
	ds_write2_b32 v14, v24, v25 offset0:148 offset1:214
	v_add_u32_e32 v14, 0xc00, v52
	s_waitcnt vmcnt(19)
	ds_write2_b32 v14, v26, v27 offset0:24 offset1:90
	s_waitcnt vmcnt(17)
	ds_write2_b32 v14, v28, v29 offset0:156 offset1:222
	v_add_u32_e32 v14, 0x1000, v52
	s_waitcnt vmcnt(15)
	ds_write2_b32 v14, v30, v31 offset0:32 offset1:98
	s_waitcnt vmcnt(13)
	ds_write2_b32 v14, v32, v33 offset0:164 offset1:230
	v_add_u32_e32 v14, 0x1400, v52
	s_waitcnt vmcnt(11)
	ds_write2_b32 v14, v34, v35 offset0:40 offset1:106
	s_waitcnt vmcnt(9)
	ds_write2_b32 v14, v36, v37 offset0:172 offset1:238
	v_add_u32_e32 v14, 0x1800, v52
	s_waitcnt vmcnt(7)
	ds_write2_b32 v14, v40, v41 offset0:48 offset1:114
	s_waitcnt vmcnt(5)
	ds_write2_b32 v14, v42, v43 offset0:180 offset1:246
	v_add_u32_e32 v14, 0x1c00, v52
	s_waitcnt vmcnt(3)
	ds_write2_b32 v14, v44, v45 offset0:56 offset1:122
	s_waitcnt vmcnt(1)
	ds_write2_b32 v14, v46, v47 offset0:188 offset1:254
	s_waitcnt lgkmcnt(0)
	ds_read2_b32 v[18:19], v54 offset0:33 offset1:41
	ds_read2_b32 v[20:21], v54 offset1:8
	ds_read2_b32 v[22:23], v54 offset0:66 offset1:74
	ds_read2_b32 v[24:25], v54 offset0:99 offset1:107
	ds_read2_b32 v[26:27], v54 offset0:132 offset1:140
	ds_read2_b32 v[28:29], v54 offset0:165 offset1:173
	ds_read2_b32 v[30:31], v54 offset0:198 offset1:206
	ds_read2_b32 v[32:33], v54 offset0:231 offset1:239
	s_lshl_b32 s26, s5, 1
	s_waitcnt lgkmcnt(6)
	v_cvt_pk_bf16_f32 v14, v20, v18
	v_or_b32_e32 v18, s4, v53
	v_lshl_add_u64 v[34:35], v[8:9], 0, s[26:27]
	v_lshlrev_b32_e32 v190, 12, v18
	s_waitcnt lgkmcnt(4)
	v_cvt_pk_bf16_f32 v15, v22, v24
	s_waitcnt lgkmcnt(2)
	v_cvt_pk_bf16_f32 v16, v26, v28
	s_waitcnt lgkmcnt(0)
	v_cvt_pk_bf16_f32 v17, v30, v32
	v_lshl_add_u64 v[36:37], v[34:35], 0, v[190:191]
	global_store_dwordx4 v[36:37], v[14:17], off nt
	v_or_b32_e32 v18, s4, v55
	v_lshlrev_b32_e32 v190, 12, v18
	v_cvt_pk_bf16_f32 v14, v21, v19
	v_cvt_pk_bf16_f32 v15, v23, v25
	v_cvt_pk_bf16_f32 v16, v27, v29
	v_cvt_pk_bf16_f32 v17, v31, v33
	ds_read2_b32 v[20:21], v54 offset0:49 offset1:57
	ds_read2_b32 v[22:23], v54 offset0:16 offset1:24
	ds_read2_b32 v[24:25], v54 offset0:82 offset1:90
	ds_read2_b32 v[26:27], v54 offset0:115 offset1:123
	ds_read2_b32 v[28:29], v54 offset0:148 offset1:156
	ds_read2_b32 v[30:31], v54 offset0:181 offset1:189
	ds_read2_b32 v[32:33], v54 offset0:214 offset1:222
	ds_read2_b32 v[36:37], v54 offset0:247 offset1:255
	v_lshl_add_u64 v[18:19], v[34:35], 0, v[190:191]
	global_store_dwordx4 v[18:19], v[14:17], off nt
	v_or_b32_e32 v18, s4, v56
	v_lshlrev_b32_e32 v190, 12, v18
	s_waitcnt lgkmcnt(6)
	v_cvt_pk_bf16_f32 v14, v22, v20
	s_waitcnt lgkmcnt(4)
	v_cvt_pk_bf16_f32 v15, v24, v26
	s_waitcnt lgkmcnt(2)
	v_cvt_pk_bf16_f32 v16, v28, v30
	s_waitcnt lgkmcnt(0)
	v_cvt_pk_bf16_f32 v17, v32, v36
	v_lshl_add_u64 v[18:19], v[34:35], 0, v[190:191]
	global_store_dwordx4 v[18:19], v[14:17], off nt
	v_or_b32_e32 v18, s4, v57
	v_lshlrev_b32_e32 v190, 12, v18
	v_cvt_pk_bf16_f32 v14, v23, v21
	v_cvt_pk_bf16_f32 v15, v25, v27
	v_cvt_pk_bf16_f32 v16, v29, v31
	v_cvt_pk_bf16_f32 v17, v33, v37
	v_lshl_add_u64 v[18:19], v[34:35], 0, v[190:191]
	global_store_dwordx4 v[18:19], v[14:17], off nt
	s_waitcnt lgkmcnt(0)

.LBB0_1075:
	s_andn2_b64 vcc, exec, s[4:5]
	s_cbranch_vccnz .LBB0_1077
	s_add_i32 s4, s1, 0xe500
	s_and_b32 s5, s4, 0xffc0
	s_and_b32 s4, s21, 0x7e0
	v_or_b32_e32 v14, s5, v51
	v_or_b32_e32 v16, s4, v50
	v_lshlrev_b32_e32 v190, 13, v14
	v_lshl_add_u64 v[14:15], s[40:41], 0, v[190:191]
	v_lshlrev_b32_e32 v190, 2, v16
	v_lshl_add_u64 v[14:15], v[14:15], 0, v[190:191]
	v_add_co_u32_e32 v16, vcc, 0x4000, v14
	global_load_dword v18, v[14:15], off nt
	s_nop 0
	v_addc_co_u32_e32 v17, vcc, 0, v15, vcc
	global_load_dword v19, v[16:17], off nt
	v_add_co_u32_e32 v16, vcc, 0x8000, v14
	s_mov_b32 s26, 0x10000
	s_nop 0
	v_addc_co_u32_e32 v17, vcc, 0, v15, vcc
	global_load_dword v20, v[16:17], off nt
	v_add_co_u32_e32 v16, vcc, 0xc000, v14
	s_nop 1
	v_addc_co_u32_e32 v17, vcc, 0, v15, vcc
	global_load_dword v21, v[16:17], off nt
	v_add_co_u32_e32 v16, vcc, s26, v14
	s_mov_b32 s26, 0x14000
	s_nop 0
	v_addc_co_u32_e32 v17, vcc, 0, v15, vcc
	global_load_dword v22, v[16:17], off nt
	v_add_co_u32_e32 v16, vcc, s26, v14
	s_mov_b32 s26, 0x18000
	s_nop 0
	v_addc_co_u32_e32 v17, vcc, 0, v15, vcc
	global_load_dword v23, v[16:17], off nt
	v_add_co_u32_e32 v16, vcc, s26, v14
	s_mov_b32 s26, 0x1c000
	s_nop 0
	v_addc_co_u32_e32 v17, vcc, 0, v15, vcc
	global_load_dword v24, v[16:17], off nt
	v_add_co_u32_e32 v16, vcc, s26, v14
	s_mov_b32 s26, 0x20000
	s_nop 0
	v_addc_co_u32_e32 v17, vcc, 0, v15, vcc
	global_load_dword v25, v[16:17], off nt
	v_add_co_u32_e32 v16, vcc, s26, v14
	s_mov_b32 s26, 0x24000
	s_nop 0
	v_addc_co_u32_e32 v17, vcc, 0, v15, vcc
	global_load_dword v26, v[16:17], off nt
	v_add_co_u32_e32 v16, vcc, s26, v14
	s_mov_b32 s26, 0x28000
	s_nop 0
	v_addc_co_u32_e32 v17, vcc, 0, v15, vcc
	global_load_dword v27, v[16:17], off nt
	v_add_co_u32_e32 v16, vcc, s26, v14
	s_mov_b32 s26, 0x2c000
	s_nop 0
	v_addc_co_u32_e32 v17, vcc, 0, v15, vcc
	global_load_dword v28, v[16:17], off nt
	v_add_co_u32_e32 v16, vcc, s26, v14
	s_mov_b32 s26, 0x30000
	s_nop 0
	v_addc_co_u32_e32 v17, vcc, 0, v15, vcc
	global_load_dword v29, v[16:17], off nt
	v_add_co_u32_e32 v16, vcc, s26, v14
	s_mov_b32 s26, 0x34000
	s_nop 0
	v_addc_co_u32_e32 v17, vcc, 0, v15, vcc
	global_load_dword v30, v[16:17], off nt
	v_add_co_u32_e32 v16, vcc, s26, v14
	s_mov_b32 s26, 0x38000
	s_nop 0
	v_addc_co_u32_e32 v17, vcc, 0, v15, vcc
	global_load_dword v31, v[16:17], off nt
	v_add_co_u32_e32 v16, vcc, s26, v14
	s_mov_b32 s26, 0x3c000
	s_nop 0
	v_addc_co_u32_e32 v17, vcc, 0, v15, vcc
	global_load_dword v32, v[16:17], off nt
	v_add_co_u32_e32 v16, vcc, s26, v14
	s_mov_b32 s26, 0x40000
	s_nop 0
	v_addc_co_u32_e32 v17, vcc, 0, v15, vcc
	global_load_dword v33, v[16:17], off nt
	v_add_co_u32_e32 v16, vcc, s26, v14
	s_mov_b32 s26, 0x44000
	s_nop 0
	v_addc_co_u32_e32 v17, vcc, 0, v15, vcc
	global_load_dword v34, v[16:17], off nt
	v_add_co_u32_e32 v16, vcc, s26, v14
	s_mov_b32 s26, 0x48000
	s_nop 0
	v_addc_co_u32_e32 v17, vcc, 0, v15, vcc
	global_load_dword v35, v[16:17], off nt
	v_add_co_u32_e32 v16, vcc, s26, v14
	s_mov_b32 s26, 0x4c000
	s_nop 0
	v_addc_co_u32_e32 v17, vcc, 0, v15, vcc
	global_load_dword v36, v[16:17], off nt
	v_add_co_u32_e32 v16, vcc, s26, v14
	s_mov_b32 s26, 0x50000
	s_nop 0
	v_addc_co_u32_e32 v17, vcc, 0, v15, vcc
	global_load_dword v37, v[16:17], off nt
	v_add_co_u32_e32 v16, vcc, s26, v14
	s_mov_b32 s26, 0x54000
	s_nop 0
	v_addc_co_u32_e32 v17, vcc, 0, v15, vcc
	global_load_dword v38, v[16:17], off nt
	v_add_co_u32_e32 v16, vcc, s26, v14
	s_mov_b32 s26, 0x58000
	s_nop 0
	v_addc_co_u32_e32 v17, vcc, 0, v15, vcc
	global_load_dword v39, v[16:17], off nt
	v_add_co_u32_e32 v16, vcc, s26, v14
	s_mov_b32 s26, 0x5c000
	s_nop 0
	v_addc_co_u32_e32 v17, vcc, 0, v15, vcc
	global_load_dword v40, v[16:17], off nt
	v_add_co_u32_e32 v16, vcc, s26, v14
	s_mov_b32 s26, 0x60000
	s_nop 0
	v_addc_co_u32_e32 v17, vcc, 0, v15, vcc
	global_load_dword v41, v[16:17], off nt
	v_add_co_u32_e32 v16, vcc, s26, v14
	s_mov_b32 s26, 0x64000
	s_nop 0
	v_addc_co_u32_e32 v17, vcc, 0, v15, vcc
	global_load_dword v42, v[16:17], off nt
	v_add_co_u32_e32 v16, vcc, s26, v14
	s_mov_b32 s26, 0x68000
	s_nop 0
	v_addc_co_u32_e32 v17, vcc, 0, v15, vcc
	global_load_dword v43, v[16:17], off nt
	v_add_co_u32_e32 v16, vcc, s26, v14
	s_mov_b32 s26, 0x6c000
	s_nop 0
	v_addc_co_u32_e32 v17, vcc, 0, v15, vcc
	global_load_dword v44, v[16:17], off nt
	v_add_co_u32_e32 v16, vcc, s26, v14
	s_mov_b32 s26, 0x70000
	s_nop 0
	v_addc_co_u32_e32 v17, vcc, 0, v15, vcc
	global_load_dword v45, v[16:17], off nt
	v_add_co_u32_e32 v16, vcc, s26, v14
	s_mov_b32 s26, 0x74000
	s_nop 0
	v_addc_co_u32_e32 v17, vcc, 0, v15, vcc
	global_load_dword v46, v[16:17], off nt
	v_add_co_u32_e32 v16, vcc, s26, v14
	s_mov_b32 s26, 0x78000
	s_nop 0
	v_addc_co_u32_e32 v17, vcc, 0, v15, vcc
	global_load_dword v47, v[16:17], off nt
	v_add_co_u32_e32 v16, vcc, s26, v14
	s_mov_b32 s26, 0x7c000
	s_nop 0
	v_addc_co_u32_e32 v17, vcc, 0, v15, vcc
	v_add_co_u32_e32 v14, vcc, s26, v14
	global_load_dword v16, v[16:17], off nt
	s_nop 0
	v_addc_co_u32_e32 v15, vcc, 0, v15, vcc
	global_load_dword v14, v[14:15], off nt
	v_add_u32_e32 v15, 0x400, v52
	s_lshl_b32 s38, s0, 1
	s_add_i32 s38, s38, s1
	s_min_i32 s38, s38, 0x62ff
	v_mov_b32_e32 v247, 0
	s_cmpk_lt_i32 s38, 0x2300
	s_cbranch_scc1 .Lpfo_wo
	s_cmpk_lt_i32 s38, 0x4300
	s_cbranch_scc1 .Lpfu_wo
	s_add_i32 s38, s38, 0xffffbd00
	s_and_b32 s39, s38, 0x7fffffc0
	s_and_b32 s38, s38, 63
	s_lshl_b32 s38, s38, 7
	v_add_u32_e32 v246, s39, v249
	v_lshlrev_b32_e32 v246, 13, v246
	v_add_u32_e32 v246, s38, v246
	v_lshl_add_u64 v[246:247], s[2:3], 0, v[246:247]
	s_branch .Lpfj_wo

.Lpfj_wo:
	global_load_dword v248, v[246:247], off
	s_waitcnt vmcnt(31)
	ds_write2_b32 v52, v18, v19 offset1:66
	s_waitcnt vmcnt(29)
	ds_write2_b32 v52, v20, v21 offset0:132 offset1:198
	s_waitcnt vmcnt(27)
	ds_write2_b32 v15, v22, v23 offset0:8 offset1:74
	s_waitcnt vmcnt(25)
	ds_write2_b32 v15, v24, v25 offset0:140 offset1:206
	v_add_u32_e32 v15, 0x800, v52
	s_waitcnt vmcnt(23)
	ds_write2_b32 v15, v26, v27 offset0:16 offset1:82
	s_waitcnt vmcnt(21)
	ds_write2_b32 v15, v28, v29 offset0:148 offset1:214
	v_add_u32_e32 v15, 0xc00, v52
	s_waitcnt vmcnt(19)
	ds_write2_b32 v15, v30, v31 offset0:24 offset1:90
	s_waitcnt vmcnt(17)
	ds_write2_b32 v15, v32, v33 offset0:156 offset1:222
	v_add_u32_e32 v15, 0x1000, v52
	s_waitcnt vmcnt(15)
	ds_write2_b32 v15, v34, v35 offset0:32 offset1:98
	s_waitcnt vmcnt(13)
	ds_write2_b32 v15, v36, v37 offset0:164 offset1:230
	v_add_u32_e32 v15, 0x1400, v52
	s_waitcnt vmcnt(11)
	ds_write2_b32 v15, v38, v39 offset0:40 offset1:106
	s_waitcnt vmcnt(9)
	ds_write2_b32 v15, v40, v41 offset0:172 offset1:238
	v_add_u32_e32 v15, 0x1800, v52
	s_waitcnt vmcnt(7)
	ds_write2_b32 v15, v42, v43 offset0:48 offset1:114
	s_waitcnt vmcnt(5)
	ds_write2_b32 v15, v44, v45 offset0:180 offset1:246
	v_add_u32_e32 v15, 0x1c00, v52
	s_waitcnt vmcnt(3)
	ds_write2_b32 v15, v46, v47 offset0:56 offset1:122
	s_waitcnt vmcnt(1)
	ds_write2_b32 v15, v16, v14 offset0:188 offset1:254
	s_waitcnt lgkmcnt(0)
	ds_read2_b32 v[20:21], v54 offset0:33 offset1:41
	ds_read2_b32 v[22:23], v54 offset1:8
	ds_read2_b32 v[24:25], v54 offset0:66 offset1:74
	ds_read2_b32 v[26:27], v54 offset0:99 offset1:107
	ds_read2_b32 v[28:29], v54 offset0:132 offset1:140
	ds_read2_b32 v[30:31], v54 offset0:165 offset1:173
	ds_read2_b32 v[32:33], v54 offset0:198 offset1:206
	ds_read2_b32 v[34:35], v54 offset0:231 offset1:239
	s_lshl_b32 s26, s5, 1
	s_waitcnt lgkmcnt(6)
	v_cvt_pk_bf16_f32 v14, v22, v20
	v_or_b32_e32 v20, s4, v53
	v_lshl_add_u64 v[18:19], v[10:11], 0, s[26:27]
	v_lshlrev_b32_e32 v190, 12, v20
	v_or_b32_e32 v20, s4, v55
	s_waitcnt lgkmcnt(4)
	v_cvt_pk_bf16_f32 v15, v24, v26
	s_waitcnt lgkmcnt(2)
	v_cvt_pk_bf16_f32 v16, v28, v30
	s_waitcnt lgkmcnt(0)
	v_cvt_pk_bf16_f32 v17, v32, v34
	v_lshl_add_u64 v[36:37], v[18:19], 0, v[190:191]
	v_lshlrev_b32_e32 v190, 12, v20
	global_store_dwordx4 v[36:37], v[14:17], off nt
	s_nop 1
	v_cvt_pk_bf16_f32 v14, v23, v21
	v_cvt_pk_bf16_f32 v15, v25, v27
	v_cvt_pk_bf16_f32 v16, v29, v31
	v_cvt_pk_bf16_f32 v17, v33, v35
	v_lshl_add_u64 v[20:21], v[18:19], 0, v[190:191]
	global_store_dwordx4 v[20:21], v[14:17], off nt
	ds_read2_b32 v[20:21], v54 offset0:49 offset1:57
	ds_read2_b32 v[22:23], v54 offset0:16 offset1:24
	ds_read2_b32 v[24:25], v54 offset0:82 offset1:90
	ds_read2_b32 v[26:27], v54 offset0:115 offset1:123
	ds_read2_b32 v[28:29], v54 offset0:148 offset1:156
	ds_read2_b32 v[30:31], v54 offset0:181 offset1:189
	ds_read2_b32 v[32:33], v54 offset0:214 offset1:222
	ds_read2_b32 v[34:35], v54 offset0:247 offset1:255
	s_waitcnt lgkmcnt(6)
	v_cvt_pk_bf16_f32 v14, v22, v20
	v_or_b32_e32 v20, s4, v56
	v_lshlrev_b32_e32 v190, 12, v20
	v_or_b32_e32 v20, s4, v57
	s_waitcnt lgkmcnt(4)
	v_cvt_pk_bf16_f32 v15, v24, v26
	s_waitcnt lgkmcnt(2)
	v_cvt_pk_bf16_f32 v16, v28, v30
	s_waitcnt lgkmcnt(0)
	v_cvt_pk_bf16_f32 v17, v32, v34
	v_lshl_add_u64 v[36:37], v[18:19], 0, v[190:191]
	v_lshlrev_b32_e32 v190, 12, v20
	global_store_dwordx4 v[36:37], v[14:17], off nt
	v_lshl_add_u64 v[18:19], v[18:19], 0, v[190:191]
	s_nop 0
	v_cvt_pk_bf16_f32 v14, v23, v21
	v_cvt_pk_bf16_f32 v15, v25, v27
	v_cvt_pk_bf16_f32 v16, v29, v31
	v_cvt_pk_bf16_f32 v17, v33, v35
	global_store_dwordx4 v[18:19], v[14:17], off nt
	s_waitcnt lgkmcnt(0)
